# SwiGLU epilogue: scalar add/mul instead of packed f32 ops (packed f32 VALU measured slow on this chip)
# baseline (speedup 1.0000x reference)
.LBB0_555:
	s_add_u32 s2, s6, 0xfffc0080
	s_addc_u32 s3, s7, -1
	s_add_i32 s77, 0, 0x10000
	v_add_u32_e32 v150, s77, v139
	ds_read_b128 v[134:137], v150
	ds_read_b128 v[142:145], v150 offset:1024
	ds_read_b128 v[146:149], v150 offset:2048
	ds_read_b128 v[150:153], v150 offset:3072
	s_cmp_eq_u32 s73, 12
	s_cselect_b32 s3, s10, s3
	s_cselect_b32 s2, s24, s2
	s_cselect_b32 s55, s25, s69
	s_cselect_b32 s54, s41, s43
	v_lshl_add_u64 v[154:155], s[6:7], 0, v[132:133]
	s_add_i32 m0, s47, 0xc000
	ds_read_b128 v[162:165], v141
	ds_read_b128 v[166:169], v141 offset:1024
	ds_read_b128 v[170:173], v141 offset:2048
	ds_read_b128 v[174:177], v141 offset:3072
	ds_read_b128 v[178:181], v141 offset:4096
	ds_read_b128 v[182:185], v141 offset:5120
	ds_read_b128 v[186:189], v141 offset:6144
	ds_read_b128 v[214:217], v141 offset:7168
	global_load_lds_dwordx4 v[154:155], off
	v_lshl_add_u64 v[154:155], s[6:7], 0, v[130:131]
	s_add_i32 m0, s47, 0xe000
	s_nop 0
	global_load_lds_dwordx4 v[154:155], off
	s_waitcnt lgkmcnt(8)
	s_barrier
	s_waitcnt lgkmcnt(0)
	s_setprio 1
	s_waitcnt lgkmcnt(0)
	v_mfma_f32_16x16x32_bf16 v[124:127], v[134:137], v[162:165], v[124:127]
	v_mfma_f32_16x16x32_bf16 v[116:119], v[146:149], v[162:165], v[116:119]
	v_mfma_f32_16x16x32_bf16 v[108:111], v[134:137], v[170:173], v[108:111]
	v_mfma_f32_16x16x32_bf16 v[100:103], v[146:149], v[170:173], v[100:103]
	v_mfma_f32_16x16x32_bf16 v[92:95], v[134:137], v[178:181], v[92:95]
	v_mfma_f32_16x16x32_bf16 v[84:87], v[146:149], v[178:181], v[84:87]
	v_mfma_f32_16x16x32_bf16 v[76:79], v[134:137], v[186:189], v[76:79]
	v_mfma_f32_16x16x32_bf16 v[68:71], v[146:149], v[186:189], v[68:71]
	v_mfma_f32_16x16x32_bf16 v[124:127], v[142:145], v[166:169], v[124:127]
	v_mfma_f32_16x16x32_bf16 v[116:119], v[150:153], v[166:169], v[116:119]
	v_mfma_f32_16x16x32_bf16 v[108:111], v[142:145], v[174:177], v[108:111]
	v_mfma_f32_16x16x32_bf16 v[100:103], v[150:153], v[174:177], v[100:103]
	v_mfma_f32_16x16x32_bf16 v[92:95], v[142:145], v[182:185], v[92:95]
	v_mfma_f32_16x16x32_bf16 v[84:87], v[150:153], v[182:185], v[84:87]
	v_mfma_f32_16x16x32_bf16 v[76:79], v[142:145], v[214:217], v[76:79]
	v_mfma_f32_16x16x32_bf16 v[68:71], v[150:153], v[214:217], v[68:71]
	s_setprio 0
	s_barrier
	s_add_i32 s80, 0, 0x14000
	v_add_u32_e32 v154, s80, v139
	s_add_i32 s77, s77, s53
	ds_read_b128 v[218:221], v154
	ds_read_b128 v[222:225], v154 offset:1024
	ds_read_b128 v[226:229], v154 offset:2048
	ds_read_b128 v[230:233], v154 offset:3072
	v_lshl_add_u64 v[154:155], s[54:55], 0, v[156:157]
	s_mov_b32 m0, s77
	v_lshl_add_u64 v[206:207], s[54:55], 0, v[128:129]
	global_load_lds_dwordx4 v[154:155], off
	s_add_i32 m0, s77, 0x2000
	s_nop 0
	global_load_lds_dwordx4 v[206:207], off
	s_barrier
	s_waitcnt lgkmcnt(0)
	s_setprio 1
	s_waitcnt lgkmcnt(0)
	v_mfma_f32_16x16x32_bf16 v[120:123], v[218:221], v[162:165], v[120:123]
	v_mfma_f32_16x16x32_bf16 v[112:115], v[226:229], v[162:165], v[112:115]
	v_mfma_f32_16x16x32_bf16 v[104:107], v[218:221], v[170:173], v[104:107]
	v_mfma_f32_16x16x32_bf16 v[96:99], v[226:229], v[170:173], v[96:99]
	v_mfma_f32_16x16x32_bf16 v[88:91], v[218:221], v[178:181], v[88:91]
	v_mfma_f32_16x16x32_bf16 v[80:83], v[226:229], v[178:181], v[80:83]
	v_mfma_f32_16x16x32_bf16 v[72:75], v[218:221], v[186:189], v[72:75]
	v_mfma_f32_16x16x32_bf16 v[64:67], v[226:229], v[186:189], v[64:67]
	v_mfma_f32_16x16x32_bf16 v[120:123], v[222:225], v[166:169], v[120:123]
	v_mfma_f32_16x16x32_bf16 v[112:115], v[230:233], v[166:169], v[112:115]
	v_mfma_f32_16x16x32_bf16 v[104:107], v[222:225], v[174:177], v[104:107]
	v_mfma_f32_16x16x32_bf16 v[96:99], v[230:233], v[174:177], v[96:99]
	v_mfma_f32_16x16x32_bf16 v[88:91], v[222:225], v[182:185], v[88:91]
	v_mfma_f32_16x16x32_bf16 v[80:83], v[230:233], v[182:185], v[80:83]
	v_mfma_f32_16x16x32_bf16 v[72:75], v[222:225], v[214:217], v[72:75]
	v_mfma_f32_16x16x32_bf16 v[64:67], v[230:233], v[214:217], v[64:67]
	s_setprio 0
	s_mov_b32 m0, s47
	v_lshl_add_u64 v[208:209], s[2:3], 0, v[156:157]
	s_barrier
	ds_read_b128 v[162:165], v141 offset:16384
	ds_read_b128 v[166:169], v141 offset:17408
	ds_read_b128 v[170:173], v141 offset:18432
	ds_read_b128 v[174:177], v141 offset:19456
	ds_read_b128 v[178:181], v141 offset:20480
	ds_read_b128 v[182:185], v141 offset:21504
	ds_read_b128 v[186:189], v141 offset:22528
	ds_read_b128 v[214:217], v141 offset:23552
	global_load_lds_dwordx4 v[208:209], off
	v_lshl_add_u64 v[234:235], s[2:3], 0, v[128:129]
	s_mov_b32 m0, s49
	s_nop 0
	global_load_lds_dwordx4 v[234:235], off
	s_barrier
	s_waitcnt lgkmcnt(0)
	s_setprio 1
	s_waitcnt lgkmcnt(0)
	v_mfma_f32_16x16x32_bf16 v[60:63], v[134:137], v[162:165], v[60:63]
	v_mfma_f32_16x16x32_bf16 v[52:55], v[146:149], v[162:165], v[52:55]
	v_mfma_f32_16x16x32_bf16 v[44:47], v[134:137], v[170:173], v[44:47]
	v_mfma_f32_16x16x32_bf16 v[36:39], v[146:149], v[170:173], v[36:39]
	v_mfma_f32_16x16x32_bf16 v[28:31], v[134:137], v[178:181], v[28:31]
	v_mfma_f32_16x16x32_bf16 v[20:23], v[146:149], v[178:181], v[20:23]
	v_mfma_f32_16x16x32_bf16 v[12:15], v[134:137], v[186:189], v[12:15]
	v_mfma_f32_16x16x32_bf16 v[4:7], v[146:149], v[186:189], v[4:7]
	v_mfma_f32_16x16x32_bf16 v[60:63], v[142:145], v[166:169], v[60:63]
	v_mfma_f32_16x16x32_bf16 v[52:55], v[150:153], v[166:169], v[52:55]
	v_mfma_f32_16x16x32_bf16 v[44:47], v[142:145], v[174:177], v[44:47]
	v_mfma_f32_16x16x32_bf16 v[36:39], v[150:153], v[174:177], v[36:39]
	v_mfma_f32_16x16x32_bf16 v[28:31], v[142:145], v[182:185], v[28:31]
	v_mfma_f32_16x16x32_bf16 v[20:23], v[150:153], v[182:185], v[20:23]
	v_mfma_f32_16x16x32_bf16 v[12:15], v[142:145], v[214:217], v[12:15]
	v_mfma_f32_16x16x32_bf16 v[4:7], v[150:153], v[214:217], v[4:7]
	s_setprio 0
	s_barrier
	s_add_u32 s78, s54, 0x40000
	s_addc_u32 s79, s55, 0
	s_add_i32 s77, s80, s53
	v_lshl_add_u64 v[134:135], s[78:79], 0, v[156:157]
	s_mov_b32 m0, s77
	s_nop 0
	global_load_lds_dwordx4 v[134:135], off
	v_lshl_add_u64 v[134:135], s[78:79], 0, v[128:129]
	s_add_i32 m0, s77, 0x2000
	s_nop 0
	global_load_lds_dwordx4 v[134:135], off
	s_waitcnt vmcnt(6)
	s_barrier
	s_setprio 1
	v_mfma_f32_16x16x32_bf16 v[56:59], v[218:221], v[162:165], v[56:59]
	v_mfma_f32_16x16x32_bf16 v[48:51], v[226:229], v[162:165], v[48:51]
	v_mfma_f32_16x16x32_bf16 v[40:43], v[218:221], v[170:173], v[40:43]
	v_mfma_f32_16x16x32_bf16 v[32:35], v[226:229], v[170:173], v[32:35]
	v_mfma_f32_16x16x32_bf16 v[24:27], v[218:221], v[178:181], v[24:27]
	v_mfma_f32_16x16x32_bf16 v[16:19], v[226:229], v[178:181], v[16:19]
	v_mfma_f32_16x16x32_bf16 v[8:11], v[218:221], v[186:189], v[8:11]
	v_mfma_f32_16x16x32_bf16 v[0:3], v[226:229], v[186:189], v[0:3]
	v_mfma_f32_16x16x32_bf16 v[56:59], v[222:225], v[166:169], v[56:59]
	v_mfma_f32_16x16x32_bf16 v[48:51], v[230:233], v[166:169], v[48:51]
	v_mfma_f32_16x16x32_bf16 v[40:43], v[222:225], v[174:177], v[40:43]
	v_mfma_f32_16x16x32_bf16 v[32:35], v[230:233], v[174:177], v[32:35]
	v_mfma_f32_16x16x32_bf16 v[24:27], v[222:225], v[182:185], v[24:27]
	v_mfma_f32_16x16x32_bf16 v[16:19], v[230:233], v[182:185], v[16:19]
	v_mfma_f32_16x16x32_bf16 v[8:11], v[222:225], v[214:217], v[8:11]
	v_mfma_f32_16x16x32_bf16 v[0:3], v[230:233], v[214:217], v[0:3]
	s_setprio 0
	s_add_i32 s77, 0, 0x18000
	v_add_u32_e32 v150, s77, v139
	s_barrier
	ds_read_b128 v[134:137], v150
	ds_read_b128 v[142:145], v150 offset:1024
	ds_read_b128 v[146:149], v150 offset:2048
	ds_read_b128 v[150:153], v150 offset:3072
	s_add_u32 s2, s2, 0x40000
	s_addc_u32 s3, s3, 0
	s_mov_b32 m0, s62
	v_lshl_add_u64 v[218:219], s[2:3], 0, v[156:157]
	ds_read_b128 v[162:165], v141 offset:32768
	ds_read_b128 v[166:169], v141 offset:33792
	ds_read_b128 v[170:173], v141 offset:34816
	ds_read_b128 v[174:177], v141 offset:35840
	ds_read_b128 v[178:181], v141 offset:36864
	ds_read_b128 v[182:185], v141 offset:37888
	ds_read_b128 v[186:189], v141 offset:38912
	ds_read_b128 v[214:217], v141 offset:39936
	global_load_lds_dwordx4 v[218:219], off
	v_lshl_add_u64 v[218:219], s[2:3], 0, v[128:129]
	s_mov_b32 m0, s63
	s_nop 0
	global_load_lds_dwordx4 v[218:219], off
	s_waitcnt lgkmcnt(8)
	s_barrier
	s_waitcnt lgkmcnt(0)
	s_setprio 1
	s_waitcnt lgkmcnt(0)
	v_mfma_f32_16x16x32_bf16 v[124:127], v[134:137], v[162:165], v[124:127]
	v_mfma_f32_16x16x32_bf16 v[116:119], v[146:149], v[162:165], v[116:119]
	v_mfma_f32_16x16x32_bf16 v[108:111], v[134:137], v[170:173], v[108:111]
	v_mfma_f32_16x16x32_bf16 v[100:103], v[146:149], v[170:173], v[100:103]
	v_mfma_f32_16x16x32_bf16 v[92:95], v[134:137], v[178:181], v[92:95]
	v_mfma_f32_16x16x32_bf16 v[84:87], v[146:149], v[178:181], v[84:87]
	v_mfma_f32_16x16x32_bf16 v[76:79], v[134:137], v[186:189], v[76:79]
	v_mfma_f32_16x16x32_bf16 v[68:71], v[146:149], v[186:189], v[68:71]
	v_mfma_f32_16x16x32_bf16 v[124:127], v[142:145], v[166:169], v[124:127]
	v_mfma_f32_16x16x32_bf16 v[116:119], v[150:153], v[166:169], v[116:119]
	v_mfma_f32_16x16x32_bf16 v[108:111], v[142:145], v[174:177], v[108:111]
	v_mfma_f32_16x16x32_bf16 v[100:103], v[150:153], v[174:177], v[100:103]
	v_mfma_f32_16x16x32_bf16 v[92:95], v[142:145], v[182:185], v[92:95]
	v_mfma_f32_16x16x32_bf16 v[84:87], v[150:153], v[182:185], v[84:87]
	v_mfma_f32_16x16x32_bf16 v[76:79], v[142:145], v[214:217], v[76:79]
	v_mfma_f32_16x16x32_bf16 v[68:71], v[150:153], v[214:217], v[68:71]
	s_setprio 0
	s_barrier
	s_add_i32 s78, 0, 0x1c000
	s_add_i32 s2, s77, s53
	v_add_u32_e32 v161, s78, v139
	v_lshl_add_u64 v[154:155], v[154:155], 0, s[50:51]
	s_mov_b32 m0, s2
	ds_read_b128 v[218:221], v161
	ds_read_b128 v[222:225], v161 offset:1024
	ds_read_b128 v[226:229], v161 offset:2048
	ds_read_b128 v[230:233], v161 offset:3072
	global_load_lds_dwordx4 v[154:155], off
	v_lshl_add_u64 v[154:155], v[206:207], 0, s[50:51]
	s_add_i32 m0, s2, 0x2000
	s_nop 0
	global_load_lds_dwordx4 v[154:155], off
	s_barrier
	s_waitcnt lgkmcnt(0)
	s_setprio 1
	s_waitcnt lgkmcnt(0)
	v_mfma_f32_16x16x32_bf16 v[120:123], v[218:221], v[162:165], v[120:123]
	v_mfma_f32_16x16x32_bf16 v[112:115], v[226:229], v[162:165], v[112:115]
	v_mfma_f32_16x16x32_bf16 v[104:107], v[218:221], v[170:173], v[104:107]
	v_mfma_f32_16x16x32_bf16 v[96:99], v[226:229], v[170:173], v[96:99]
	v_mfma_f32_16x16x32_bf16 v[88:91], v[218:221], v[178:181], v[88:91]
	v_mfma_f32_16x16x32_bf16 v[80:83], v[226:229], v[178:181], v[80:83]
	v_mfma_f32_16x16x32_bf16 v[72:75], v[218:221], v[186:189], v[72:75]
	v_mfma_f32_16x16x32_bf16 v[64:67], v[226:229], v[186:189], v[64:67]
	v_mfma_f32_16x16x32_bf16 v[120:123], v[222:225], v[166:169], v[120:123]
	v_mfma_f32_16x16x32_bf16 v[112:115], v[230:233], v[166:169], v[112:115]
	v_mfma_f32_16x16x32_bf16 v[104:107], v[222:225], v[174:177], v[104:107]
	v_mfma_f32_16x16x32_bf16 v[96:99], v[230:233], v[174:177], v[96:99]
	v_mfma_f32_16x16x32_bf16 v[88:91], v[222:225], v[182:185], v[88:91]
	v_mfma_f32_16x16x32_bf16 v[80:83], v[230:233], v[182:185], v[80:83]
	v_mfma_f32_16x16x32_bf16 v[72:75], v[222:225], v[214:217], v[72:75]
	v_mfma_f32_16x16x32_bf16 v[64:67], v[230:233], v[214:217], v[64:67]
	s_setprio 0
	s_mov_b32 m0, s66
	v_lshl_add_u64 v[154:155], v[208:209], 0, s[50:51]
	s_barrier
	ds_read_b128 v[162:165], v141 offset:49152
	ds_read_b128 v[166:169], v141 offset:50176
	ds_read_b128 v[170:173], v141 offset:51200
	ds_read_b128 v[174:177], v141 offset:52224
	ds_read_b128 v[178:181], v141 offset:53248
	ds_read_b128 v[182:185], v141 offset:54272
	ds_read_b128 v[186:189], v141 offset:55296
	ds_read_b128 v[214:217], v141 offset:56320
	global_load_lds_dwordx4 v[154:155], off
	v_lshl_add_u64 v[154:155], v[234:235], 0, s[50:51]
	s_mov_b32 m0, s67
	s_nop 0
	global_load_lds_dwordx4 v[154:155], off
	s_barrier
	s_waitcnt lgkmcnt(0)
	s_setprio 1
	s_waitcnt lgkmcnt(0)
	v_mfma_f32_16x16x32_bf16 v[60:63], v[134:137], v[162:165], v[60:63]
	v_mfma_f32_16x16x32_bf16 v[52:55], v[146:149], v[162:165], v[52:55]
	v_mfma_f32_16x16x32_bf16 v[44:47], v[134:137], v[170:173], v[44:47]
	v_mfma_f32_16x16x32_bf16 v[36:39], v[146:149], v[170:173], v[36:39]
	v_mfma_f32_16x16x32_bf16 v[28:31], v[134:137], v[178:181], v[28:31]
	v_mfma_f32_16x16x32_bf16 v[20:23], v[146:149], v[178:181], v[20:23]
	v_mfma_f32_16x16x32_bf16 v[12:15], v[134:137], v[186:189], v[12:15]
	v_mfma_f32_16x16x32_bf16 v[4:7], v[146:149], v[186:189], v[4:7]
	v_mfma_f32_16x16x32_bf16 v[60:63], v[142:145], v[166:169], v[60:63]
	v_mfma_f32_16x16x32_bf16 v[52:55], v[150:153], v[166:169], v[52:55]
	v_mfma_f32_16x16x32_bf16 v[44:47], v[142:145], v[174:177], v[44:47]
	v_mfma_f32_16x16x32_bf16 v[36:39], v[150:153], v[174:177], v[36:39]
	v_mfma_f32_16x16x32_bf16 v[28:31], v[142:145], v[182:185], v[28:31]
	v_mfma_f32_16x16x32_bf16 v[20:23], v[150:153], v[182:185], v[20:23]
	v_mfma_f32_16x16x32_bf16 v[12:15], v[142:145], v[214:217], v[12:15]
	v_mfma_f32_16x16x32_bf16 v[4:7], v[150:153], v[214:217], v[4:7]
	s_setprio 0
	s_barrier
	s_add_u32 s2, s54, 0x40080
	s_addc_u32 s3, s55, 0
	s_add_i32 s54, s78, s53
	v_lshl_add_u64 v[134:135], s[2:3], 0, v[156:157]
	s_mov_b32 m0, s54
	s_nop 0
	global_load_lds_dwordx4 v[134:135], off
	v_lshl_add_u64 v[134:135], s[2:3], 0, v[128:129]
	s_add_i32 m0, s54, 0x2000
	s_nop 0
	global_load_lds_dwordx4 v[134:135], off
	s_waitcnt vmcnt(6)
	s_barrier
	s_setprio 1
	v_mfma_f32_16x16x32_bf16 v[56:59], v[218:221], v[162:165], v[56:59]
	v_mfma_f32_16x16x32_bf16 v[48:51], v[226:229], v[162:165], v[48:51]
	v_mfma_f32_16x16x32_bf16 v[40:43], v[218:221], v[170:173], v[40:43]
	v_mfma_f32_16x16x32_bf16 v[32:35], v[226:229], v[170:173], v[32:35]
	v_mfma_f32_16x16x32_bf16 v[24:27], v[218:221], v[178:181], v[24:27]
	v_mfma_f32_16x16x32_bf16 v[16:19], v[226:229], v[178:181], v[16:19]
	v_mfma_f32_16x16x32_bf16 v[8:11], v[218:221], v[186:189], v[8:11]
	v_mfma_f32_16x16x32_bf16 v[0:3], v[226:229], v[186:189], v[0:3]
	v_mfma_f32_16x16x32_bf16 v[56:59], v[222:225], v[166:169], v[56:59]
	v_mfma_f32_16x16x32_bf16 v[48:51], v[230:233], v[166:169], v[48:51]
	v_mfma_f32_16x16x32_bf16 v[40:43], v[222:225], v[174:177], v[40:43]
	v_mfma_f32_16x16x32_bf16 v[32:35], v[230:233], v[174:177], v[32:35]
	v_mfma_f32_16x16x32_bf16 v[24:27], v[222:225], v[182:185], v[24:27]
	v_mfma_f32_16x16x32_bf16 v[16:19], v[230:233], v[182:185], v[16:19]
	v_mfma_f32_16x16x32_bf16 v[8:11], v[222:225], v[214:217], v[8:11]
	v_mfma_f32_16x16x32_bf16 v[0:3], v[230:233], v[214:217], v[0:3]
	s_setprio 0
	s_add_i32 s73, s73, 2
	s_add_u32 s43, s43, 0x100
	s_addc_u32 s69, s69, 0
	s_add_u32 s6, s6, 0x100
	s_addc_u32 s7, s7, 0
	s_cmp_gt_u32 s73, 13
	s_barrier
	s_cbranch_scc0 .LBB0_555
	v_lshl_or_b32 v136, s46, 7, v140
	v_lshl_add_u32 v142, s48, 8, v138
	v_ashrrev_i32_e32 v137, 31, v136
	v_mov_b64_e32 v[134:135], s[30:31]
	v_lshlrev_b64 v[136:137], 1, v[136:137]
	s_and_b64 vcc, exec, s[38:39]
	s_mov_b32 s48, s42
	s_mov_b32 s46, s40
	v_mad_i64_i32 v[144:145], s[2:3], v142, s33, v[134:135]
	v_or_b32_e32 v186, 16, v142
	v_mul_f32_e32 v162, 0xbfb8aa3b, v124
	v_mad_i64_i32 v[186:187], s[2:3], v186, s33, v[134:135]
	v_mul_f32_e32 v163, 0xbfb8aa3b, v125
	v_mul_f32_e32 v170, 0xbfb8aa3b, v108
	v_mul_f32_e32 v164, 0xbfb8aa3b, v126
	v_mul_f32_e32 v171, 0xbfb8aa3b, v109
	v_mul_f32_e32 v165, 0xbfb8aa3b, v127
	v_mul_f32_e32 v172, 0xbfb8aa3b, v110
	v_mul_f32_e32 v166, 0xbfb8aa3b, v116
	v_mul_f32_e32 v173, 0xbfb8aa3b, v111
	v_mul_f32_e32 v167, 0xbfb8aa3b, v117
	v_mul_f32_e32 v174, 0xbfb8aa3b, v100
	v_mul_f32_e32 v168, 0xbfb8aa3b, v118
	v_mul_f32_e32 v175, 0xbfb8aa3b, v101
	v_mul_f32_e32 v169, 0xbfb8aa3b, v119
	v_mul_f32_e32 v176, 0xbfb8aa3b, v102
	v_lshl_add_u64 v[144:145], v[144:145], 0, v[136:137]
	v_mul_f32_e32 v177, 0xbfb8aa3b, v103
	v_exp_f32_e32 v162, v162
	v_lshl_add_u64 v[186:187], v[186:187], 0, v[136:137]
	v_exp_f32_e32 v163, v163
	v_exp_f32_e32 v170, v170
	v_exp_f32_e32 v164, v164
	v_exp_f32_e32 v171, v171
	v_exp_f32_e32 v165, v165
	v_exp_f32_e32 v172, v172
	v_exp_f32_e32 v166, v166
	v_exp_f32_e32 v173, v173
	v_exp_f32_e32 v167, v167
	v_exp_f32_e32 v174, v174
	v_exp_f32_e32 v168, v168
	v_exp_f32_e32 v175, v175
	v_exp_f32_e32 v169, v169
	v_exp_f32_e32 v176, v176
	v_add_f32_e32 v162, 1.0, v162
	v_exp_f32_e32 v177, v177
	v_add_f32_e32 v163, 1.0, v163
	v_add_f32_e32 v170, 1.0, v170
	v_add_f32_e32 v164, 1.0, v164
	v_add_f32_e32 v171, 1.0, v171
	v_add_f32_e32 v165, 1.0, v165
	v_add_f32_e32 v172, 1.0, v172
	v_add_f32_e32 v166, 1.0, v166
	v_add_f32_e32 v173, 1.0, v173
	v_add_f32_e32 v167, 1.0, v167
	v_add_f32_e32 v174, 1.0, v174
	v_add_f32_e32 v168, 1.0, v168
	v_add_f32_e32 v175, 1.0, v175
	v_add_f32_e32 v169, 1.0, v169
	v_add_f32_e32 v176, 1.0, v176
	v_rcp_f32_e32 v162, v162
	v_add_f32_e32 v177, 1.0, v177
	v_rcp_f32_e32 v163, v163
	v_rcp_f32_e32 v170, v170
	v_rcp_f32_e32 v164, v164
	v_rcp_f32_e32 v171, v171
	v_rcp_f32_e32 v165, v165
	v_rcp_f32_e32 v172, v172
	v_rcp_f32_e32 v166, v166
	v_rcp_f32_e32 v173, v173
	v_rcp_f32_e32 v167, v167
	v_rcp_f32_e32 v174, v174
	v_rcp_f32_e32 v168, v168
	v_rcp_f32_e32 v175, v175
	v_rcp_f32_e32 v169, v169
	v_rcp_f32_e32 v176, v176
	v_mul_f32_e32 v162, v124, v162
	v_rcp_f32_e32 v177, v177
	v_mul_f32_e32 v163, v125, v163
	v_mul_f32_e32 v170, v108, v170
	v_mul_f32_e32 v164, v126, v164
	v_mul_f32_e32 v171, v109, v171
	v_mul_f32_e32 v165, v127, v165
	v_mul_f32_e32 v172, v110, v172
	v_mul_f32_e32 v166, v116, v166
	v_mul_f32_e32 v173, v111, v173
	v_mul_f32_e32 v167, v117, v167
	v_mul_f32_e32 v174, v100, v174
	v_mul_f32_e32 v168, v118, v168
	v_mul_f32_e32 v175, v101, v175
	v_mul_f32_e32 v169, v119, v169
	v_mul_f32_e32 v176, v102, v176
	v_mul_f32_e32 v162, v162, v120
	v_mul_f32_e32 v177, v103, v177
	v_mul_f32_e32 v163, v163, v121
	v_mul_f32_e32 v170, v170, v104
	v_mul_f32_e32 v164, v164, v122
	v_mul_f32_e32 v171, v171, v105
	v_mul_f32_e32 v165, v165, v123
	v_mul_f32_e32 v172, v172, v106
	v_mul_f32_e32 v166, v166, v112
	v_mul_f32_e32 v173, v173, v107
	v_mul_f32_e32 v167, v167, v113
	v_mul_f32_e32 v174, v174, v96
	v_mul_f32_e32 v168, v168, v114
	v_mul_f32_e32 v175, v175, v97
	v_mul_f32_e32 v169, v169, v115
	v_mul_f32_e32 v176, v176, v98
	v_cvt_pk_bf16_f32 v178, v162, v163
	v_mul_f32_e32 v177, v177, v99
	v_cvt_pk_bf16_f32 v179, v164, v165
	v_cvt_pk_bf16_f32 v182, v170, v171
	v_cvt_pk_bf16_f32 v180, v166, v167
	v_cvt_pk_bf16_f32 v183, v172, v173
	v_cvt_pk_bf16_f32 v181, v168, v169
	v_cvt_pk_bf16_f32 v184, v174, v175
	global_store_dwordx4 v[144:145], v[178:181], off
	v_cvt_pk_bf16_f32 v185, v176, v177
	global_store_dwordx4 v[186:187], v[182:185], off
	v_or_b32_e32 v144, 32, v142
	v_or_b32_e32 v186, 48, v142
	v_mad_i64_i32 v[144:145], s[2:3], v144, s33, v[134:135]
	v_mad_i64_i32 v[186:187], s[2:3], v186, s33, v[134:135]
	v_mul_f32_e32 v162, 0xbfb8aa3b, v92
	v_mul_f32_e32 v170, 0xbfb8aa3b, v76
	v_mul_f32_e32 v163, 0xbfb8aa3b, v93
	v_mul_f32_e32 v171, 0xbfb8aa3b, v77
	v_mul_f32_e32 v164, 0xbfb8aa3b, v94
	v_mul_f32_e32 v172, 0xbfb8aa3b, v78
	v_mul_f32_e32 v165, 0xbfb8aa3b, v95
	v_mul_f32_e32 v173, 0xbfb8aa3b, v79
	v_mul_f32_e32 v166, 0xbfb8aa3b, v84
	v_mul_f32_e32 v174, 0xbfb8aa3b, v68
	v_mul_f32_e32 v167, 0xbfb8aa3b, v85
	v_mul_f32_e32 v175, 0xbfb8aa3b, v69
	v_mul_f32_e32 v168, 0xbfb8aa3b, v86
	v_mul_f32_e32 v176, 0xbfb8aa3b, v70
	v_mul_f32_e32 v169, 0xbfb8aa3b, v87
	v_mul_f32_e32 v177, 0xbfb8aa3b, v71
	v_lshl_add_u64 v[144:145], v[144:145], 0, v[136:137]
	v_lshl_add_u64 v[186:187], v[186:187], 0, v[136:137]
	v_exp_f32_e32 v162, v162
	v_exp_f32_e32 v170, v170
	v_exp_f32_e32 v163, v163
	v_exp_f32_e32 v171, v171
	v_exp_f32_e32 v164, v164
	v_exp_f32_e32 v172, v172
	v_exp_f32_e32 v165, v165
	v_exp_f32_e32 v173, v173
	v_exp_f32_e32 v166, v166
	v_exp_f32_e32 v174, v174
	v_exp_f32_e32 v167, v167
	v_exp_f32_e32 v175, v175
	v_exp_f32_e32 v168, v168
	v_exp_f32_e32 v176, v176
	v_exp_f32_e32 v169, v169
	v_exp_f32_e32 v177, v177
	v_add_f32_e32 v162, 1.0, v162
	v_add_f32_e32 v170, 1.0, v170
	v_add_f32_e32 v163, 1.0, v163
	v_add_f32_e32 v171, 1.0, v171
	v_add_f32_e32 v164, 1.0, v164
	v_add_f32_e32 v172, 1.0, v172
	v_add_f32_e32 v165, 1.0, v165
	v_add_f32_e32 v173, 1.0, v173
	v_add_f32_e32 v166, 1.0, v166
	v_add_f32_e32 v174, 1.0, v174
	v_add_f32_e32 v167, 1.0, v167
	v_add_f32_e32 v175, 1.0, v175
	v_add_f32_e32 v168, 1.0, v168
	v_add_f32_e32 v176, 1.0, v176
	v_add_f32_e32 v169, 1.0, v169
	v_add_f32_e32 v177, 1.0, v177
	v_rcp_f32_e32 v162, v162
	v_rcp_f32_e32 v170, v170
	v_rcp_f32_e32 v163, v163
	v_rcp_f32_e32 v171, v171
	v_rcp_f32_e32 v164, v164
	v_rcp_f32_e32 v172, v172
	v_rcp_f32_e32 v165, v165
	v_rcp_f32_e32 v173, v173
	v_rcp_f32_e32 v166, v166
	v_rcp_f32_e32 v174, v174
	v_rcp_f32_e32 v167, v167
	v_rcp_f32_e32 v175, v175
	v_rcp_f32_e32 v168, v168
	v_rcp_f32_e32 v176, v176
	v_rcp_f32_e32 v169, v169
	v_rcp_f32_e32 v177, v177
	v_mul_f32_e32 v162, v92, v162
	v_mul_f32_e32 v170, v76, v170
	v_mul_f32_e32 v163, v93, v163
	v_mul_f32_e32 v171, v77, v171
	v_mul_f32_e32 v164, v94, v164
	v_mul_f32_e32 v172, v78, v172
	v_mul_f32_e32 v165, v95, v165
	v_mul_f32_e32 v173, v79, v173
	v_mul_f32_e32 v166, v84, v166
	v_mul_f32_e32 v174, v68, v174
	v_mul_f32_e32 v167, v85, v167
	v_mul_f32_e32 v175, v69, v175
	v_mul_f32_e32 v168, v86, v168
	v_mul_f32_e32 v176, v70, v176
	v_mul_f32_e32 v169, v87, v169
	v_mul_f32_e32 v177, v71, v177
	v_mul_f32_e32 v162, v162, v88
	v_mul_f32_e32 v170, v170, v72
	v_mul_f32_e32 v163, v163, v89
	v_mul_f32_e32 v171, v171, v73
	v_mul_f32_e32 v164, v164, v90
	v_mul_f32_e32 v172, v172, v74
	v_mul_f32_e32 v165, v165, v91
	v_mul_f32_e32 v173, v173, v75
	v_mul_f32_e32 v166, v166, v80
	v_mul_f32_e32 v174, v174, v64
	v_mul_f32_e32 v167, v167, v81
	v_mul_f32_e32 v175, v175, v65
	v_mul_f32_e32 v168, v168, v82
	v_mul_f32_e32 v176, v176, v66
	v_mul_f32_e32 v169, v169, v83
	v_mul_f32_e32 v177, v177, v67
	v_cvt_pk_bf16_f32 v178, v162, v163
	v_cvt_pk_bf16_f32 v182, v170, v171
	v_cvt_pk_bf16_f32 v179, v164, v165
	v_cvt_pk_bf16_f32 v183, v172, v173
	v_cvt_pk_bf16_f32 v180, v166, v167
	v_cvt_pk_bf16_f32 v184, v174, v175
	v_cvt_pk_bf16_f32 v181, v168, v169
	v_cvt_pk_bf16_f32 v185, v176, v177
	global_store_dwordx4 v[144:145], v[178:181], off
	global_store_dwordx4 v[186:187], v[182:185], off
	v_add_u32_e32 v144, 0x80, v142
	v_add_u32_e32 v186, 0x90, v142
	v_mad_i64_i32 v[144:145], s[2:3], v144, s33, v[134:135]
	v_mad_i64_i32 v[186:187], s[2:3], v186, s33, v[134:135]
	v_mul_f32_e32 v162, 0xbfb8aa3b, v60
	v_mul_f32_e32 v170, 0xbfb8aa3b, v44
	v_mul_f32_e32 v163, 0xbfb8aa3b, v61
	v_mul_f32_e32 v171, 0xbfb8aa3b, v45
	v_mul_f32_e32 v164, 0xbfb8aa3b, v62
	v_mul_f32_e32 v172, 0xbfb8aa3b, v46
	v_mul_f32_e32 v165, 0xbfb8aa3b, v63
	v_mul_f32_e32 v173, 0xbfb8aa3b, v47
	v_mul_f32_e32 v166, 0xbfb8aa3b, v52
	v_mul_f32_e32 v174, 0xbfb8aa3b, v36
	v_mul_f32_e32 v167, 0xbfb8aa3b, v53
	v_mul_f32_e32 v175, 0xbfb8aa3b, v37
	v_mul_f32_e32 v168, 0xbfb8aa3b, v54
	v_mul_f32_e32 v176, 0xbfb8aa3b, v38
	v_mul_f32_e32 v169, 0xbfb8aa3b, v55
	v_mul_f32_e32 v177, 0xbfb8aa3b, v39
	v_lshl_add_u64 v[144:145], v[144:145], 0, v[136:137]
	v_lshl_add_u64 v[186:187], v[186:187], 0, v[136:137]
	v_exp_f32_e32 v162, v162
	v_exp_f32_e32 v170, v170
	v_exp_f32_e32 v163, v163
	v_exp_f32_e32 v171, v171
	v_exp_f32_e32 v164, v164
	v_exp_f32_e32 v172, v172
	v_exp_f32_e32 v165, v165
	v_exp_f32_e32 v173, v173
	v_exp_f32_e32 v166, v166
	v_exp_f32_e32 v174, v174
	v_exp_f32_e32 v167, v167
	v_exp_f32_e32 v175, v175
	v_exp_f32_e32 v168, v168
	v_exp_f32_e32 v176, v176
	v_exp_f32_e32 v169, v169
	v_exp_f32_e32 v177, v177
	v_add_f32_e32 v162, 1.0, v162
	v_add_f32_e32 v170, 1.0, v170
	v_add_f32_e32 v163, 1.0, v163
	v_add_f32_e32 v171, 1.0, v171
	v_add_f32_e32 v164, 1.0, v164
	v_add_f32_e32 v172, 1.0, v172
	v_add_f32_e32 v165, 1.0, v165
	v_add_f32_e32 v173, 1.0, v173
	v_add_f32_e32 v166, 1.0, v166
	v_add_f32_e32 v174, 1.0, v174
	v_add_f32_e32 v167, 1.0, v167
	v_add_f32_e32 v175, 1.0, v175
	v_add_f32_e32 v168, 1.0, v168
	v_add_f32_e32 v176, 1.0, v176
	v_add_f32_e32 v169, 1.0, v169
	v_add_f32_e32 v177, 1.0, v177
	v_rcp_f32_e32 v162, v162
	v_rcp_f32_e32 v170, v170
	v_rcp_f32_e32 v163, v163
	v_rcp_f32_e32 v171, v171
	v_rcp_f32_e32 v164, v164
	v_rcp_f32_e32 v172, v172
	v_rcp_f32_e32 v165, v165
	v_rcp_f32_e32 v173, v173
	v_rcp_f32_e32 v166, v166
	v_rcp_f32_e32 v174, v174
	v_rcp_f32_e32 v167, v167
	v_rcp_f32_e32 v175, v175
	v_rcp_f32_e32 v168, v168
	v_rcp_f32_e32 v176, v176
	v_rcp_f32_e32 v169, v169
	v_rcp_f32_e32 v177, v177
	v_mul_f32_e32 v162, v60, v162
	v_mul_f32_e32 v170, v44, v170
	v_mul_f32_e32 v163, v61, v163
	v_mul_f32_e32 v171, v45, v171
	v_mul_f32_e32 v164, v62, v164
	v_mul_f32_e32 v172, v46, v172
	v_mul_f32_e32 v165, v63, v165
	v_mul_f32_e32 v173, v47, v173
	v_mul_f32_e32 v166, v52, v166
	v_mul_f32_e32 v174, v36, v174
	v_mul_f32_e32 v167, v53, v167
	v_mul_f32_e32 v175, v37, v175
	v_mul_f32_e32 v168, v54, v168
	v_mul_f32_e32 v176, v38, v176
	v_mul_f32_e32 v169, v55, v169
	v_mul_f32_e32 v177, v39, v177
	v_mul_f32_e32 v162, v162, v56
	v_mul_f32_e32 v170, v170, v40
	v_mul_f32_e32 v163, v163, v57
	v_mul_f32_e32 v171, v171, v41
	v_mul_f32_e32 v164, v164, v58
	v_mul_f32_e32 v172, v172, v42
	v_mul_f32_e32 v165, v165, v59
	v_mul_f32_e32 v173, v173, v43
	v_mul_f32_e32 v166, v166, v48
	v_mul_f32_e32 v174, v174, v32
	v_mul_f32_e32 v167, v167, v49
	v_mul_f32_e32 v175, v175, v33
	v_mul_f32_e32 v168, v168, v50
	v_mul_f32_e32 v176, v176, v34
	v_mul_f32_e32 v169, v169, v51
	v_mul_f32_e32 v177, v177, v35
	v_cvt_pk_bf16_f32 v178, v162, v163
	v_cvt_pk_bf16_f32 v182, v170, v171
	v_cvt_pk_bf16_f32 v179, v164, v165
	v_cvt_pk_bf16_f32 v183, v172, v173
	v_cvt_pk_bf16_f32 v180, v166, v167
	v_cvt_pk_bf16_f32 v184, v174, v175
	v_cvt_pk_bf16_f32 v181, v168, v169
	v_cvt_pk_bf16_f32 v185, v176, v177
	global_store_dwordx4 v[144:145], v[178:181], off
	global_store_dwordx4 v[186:187], v[182:185], off
	v_add_u32_e32 v144, 0xa0, v142
	v_add_u32_e32 v186, 0xb0, v142
	v_mad_i64_i32 v[144:145], s[2:3], v144, s33, v[134:135]
	v_mad_i64_i32 v[186:187], s[2:3], v186, s33, v[134:135]
	v_mul_f32_e32 v162, 0xbfb8aa3b, v28
	v_mul_f32_e32 v170, 0xbfb8aa3b, v12
	v_mul_f32_e32 v163, 0xbfb8aa3b, v29
	v_mul_f32_e32 v171, 0xbfb8aa3b, v13
	v_mul_f32_e32 v164, 0xbfb8aa3b, v30
	v_mul_f32_e32 v172, 0xbfb8aa3b, v14
	v_mul_f32_e32 v165, 0xbfb8aa3b, v31
	v_mul_f32_e32 v173, 0xbfb8aa3b, v15
	v_mul_f32_e32 v166, 0xbfb8aa3b, v20
	v_mul_f32_e32 v174, 0xbfb8aa3b, v4
	v_mul_f32_e32 v167, 0xbfb8aa3b, v21
	v_mul_f32_e32 v175, 0xbfb8aa3b, v5
	v_mul_f32_e32 v168, 0xbfb8aa3b, v22
	v_mul_f32_e32 v176, 0xbfb8aa3b, v6
	v_mul_f32_e32 v169, 0xbfb8aa3b, v23
	v_mul_f32_e32 v177, 0xbfb8aa3b, v7
	v_lshl_add_u64 v[144:145], v[144:145], 0, v[136:137]
	v_lshl_add_u64 v[186:187], v[186:187], 0, v[136:137]
	v_exp_f32_e32 v162, v162
	v_exp_f32_e32 v170, v170
	v_exp_f32_e32 v163, v163
	v_exp_f32_e32 v171, v171
	v_exp_f32_e32 v164, v164
	v_exp_f32_e32 v172, v172
	v_exp_f32_e32 v165, v165
	v_exp_f32_e32 v173, v173
	v_exp_f32_e32 v166, v166
	v_exp_f32_e32 v174, v174
	v_exp_f32_e32 v167, v167
	v_exp_f32_e32 v175, v175
	v_exp_f32_e32 v168, v168
	v_exp_f32_e32 v176, v176
	v_exp_f32_e32 v169, v169
	v_exp_f32_e32 v177, v177
	v_add_f32_e32 v162, 1.0, v162
	v_add_f32_e32 v170, 1.0, v170
	v_add_f32_e32 v163, 1.0, v163
	v_add_f32_e32 v171, 1.0, v171
	v_add_f32_e32 v164, 1.0, v164
	v_add_f32_e32 v172, 1.0, v172
	v_add_f32_e32 v165, 1.0, v165
	v_add_f32_e32 v173, 1.0, v173
	v_add_f32_e32 v166, 1.0, v166
	v_add_f32_e32 v174, 1.0, v174
	v_add_f32_e32 v167, 1.0, v167
	v_add_f32_e32 v175, 1.0, v175
	v_add_f32_e32 v168, 1.0, v168
	v_add_f32_e32 v176, 1.0, v176
	v_add_f32_e32 v169, 1.0, v169
	v_add_f32_e32 v177, 1.0, v177
	v_rcp_f32_e32 v162, v162
	v_rcp_f32_e32 v170, v170
	v_rcp_f32_e32 v163, v163
	v_rcp_f32_e32 v171, v171
	v_rcp_f32_e32 v164, v164
	v_rcp_f32_e32 v172, v172
	v_rcp_f32_e32 v165, v165
	v_rcp_f32_e32 v173, v173
	v_rcp_f32_e32 v166, v166
	v_rcp_f32_e32 v174, v174
	v_rcp_f32_e32 v167, v167
	v_rcp_f32_e32 v175, v175
	v_rcp_f32_e32 v168, v168
	v_rcp_f32_e32 v176, v176
	v_rcp_f32_e32 v169, v169
	v_rcp_f32_e32 v177, v177
	v_mul_f32_e32 v162, v28, v162
	v_mul_f32_e32 v170, v12, v170
	v_mul_f32_e32 v163, v29, v163
	v_mul_f32_e32 v171, v13, v171
	v_mul_f32_e32 v164, v30, v164
	v_mul_f32_e32 v172, v14, v172
	v_mul_f32_e32 v165, v31, v165
	v_mul_f32_e32 v173, v15, v173
	v_mul_f32_e32 v166, v20, v166
	v_mul_f32_e32 v174, v4, v174
	v_mul_f32_e32 v167, v21, v167
	v_mul_f32_e32 v175, v5, v175
	v_mul_f32_e32 v168, v22, v168
	v_mul_f32_e32 v176, v6, v176
	v_mul_f32_e32 v169, v23, v169
	v_mul_f32_e32 v177, v7, v177
	v_mul_f32_e32 v162, v162, v24
	v_mul_f32_e32 v170, v170, v8
	v_mul_f32_e32 v163, v163, v25
	v_mul_f32_e32 v171, v171, v9
	v_mul_f32_e32 v164, v164, v26
	v_mul_f32_e32 v172, v172, v10
	v_mul_f32_e32 v165, v165, v27
	v_mul_f32_e32 v173, v173, v11
	v_mul_f32_e32 v166, v166, v16
	v_mul_f32_e32 v174, v174, v0
	v_mul_f32_e32 v167, v167, v17
	v_mul_f32_e32 v175, v175, v1
	v_mul_f32_e32 v168, v168, v18
	v_mul_f32_e32 v176, v176, v2
	v_mul_f32_e32 v169, v169, v19
	v_mul_f32_e32 v177, v177, v3
	v_cvt_pk_bf16_f32 v178, v162, v163
	v_cvt_pk_bf16_f32 v182, v170, v171
	v_cvt_pk_bf16_f32 v179, v164, v165
	v_cvt_pk_bf16_f32 v183, v172, v173
	v_cvt_pk_bf16_f32 v180, v166, v167
	v_cvt_pk_bf16_f32 v184, v174, v175
	v_cvt_pk_bf16_f32 v181, v168, v169
	v_cvt_pk_bf16_f32 v185, v176, v177
	global_store_dwordx4 v[144:145], v[178:181], off
	global_store_dwordx4 v[186:187], v[182:185], off
	s_cbranch_vccz .LBB0_554
	s_waitcnt vmcnt(0)
	s_cmpk_gt_u32 s21, 0xff
	s_cbranch_scc1 .LBB0_559
	s_barrier
